# stick-breaking tile loop: 74 packed f32 VOP3P ops split into single ops (bit-identical)
# baseline (speedup 1.0000x reference)
.LBB0_465:
	s_cmp_ge_i32 s23, s4
	s_cselect_b64 s[16:17], -1, 0
	s_or_b64 s[16:17], s[16:17], s[14:15]
	s_and_b64 vcc, exec, s[16:17]
	s_cbranch_vccnz .LBB0_467
	v_add3_u32 v130, s18, v192, v205
	ds_read_b128 v[64:67], v130 offset:8704
	ds_read_b128 v[132:135], v130 offset:8736
	v_or_b32_e32 v163, s23, v200
	v_add3_u32 v207, s22, v204, v206
	s_waitcnt lgkmcnt(1)
	v_mfma_f32_32x32x16_bf16 v[66:81], v[64:67], v[82:85], 0
	s_waitcnt lgkmcnt(0)
	v_mfma_f32_32x32x16_bf16 v[66:81], v[132:135], v[86:89], v[66:81]
	ds_read_b128 v[132:135], v130 offset:8768
	ds_read_b128 v[136:139], v130 offset:8800
	s_waitcnt lgkmcnt(1)
	v_mfma_f32_32x32x16_bf16 v[66:81], v[132:135], v[90:93], v[66:81]
	s_waitcnt lgkmcnt(0)
	v_mfma_f32_32x32x16_bf16 v[66:81], v[136:139], v[94:97], v[66:81]
	ds_read_b128 v[132:135], v130 offset:8832
	ds_read_b128 v[136:139], v130 offset:8864
	s_waitcnt lgkmcnt(1)
	v_mfma_f32_32x32x16_bf16 v[66:81], v[132:135], v[98:101], v[66:81]
	s_waitcnt lgkmcnt(0)
	v_mfma_f32_32x32x16_bf16 v[66:81], v[136:139], v[102:105], v[66:81]
	ds_read_b128 v[132:135], v130 offset:8896
	ds_read_b128 v[136:139], v130 offset:8928
	ds_read_b128 v[208:211], v130 offset:224
	s_waitcnt lgkmcnt(2)
	v_mfma_f32_32x32x16_bf16 v[66:81], v[132:135], v[106:109], v[66:81]
	s_waitcnt lgkmcnt(1)
	v_mfma_f32_32x32x16_bf16 v[66:81], v[136:139], v[110:113], v[66:81]
	s_nop 11
	v_mov_b32_e32 v64, v66
	v_mov_b32_e32 v65, v68
	v_mov_b32_e32 v68, v67
	v_mul_f32_e32 v132, s68, v64
	v_mul_f32_e32 v133, s68, v65
	v_mov_b32_e32 v66, v70
	v_mul_f32_e32 v134, s68, v68
	v_mul_f32_e32 v135, s68, v69
	v_mul_f32_e64 v70, |v132|, s54
	v_mov_b32_e32 v67, v72
	v_mul_f32_e64 v72, |v134|, s54
	v_exp_f32_e32 v70, v70
	v_mul_f32_e64 v131, |v133|, s54
	v_exp_f32_e32 v72, v72
	v_mul_f32_e64 v138, |v135|, s54
	v_exp_f32_e32 v131, v131
	v_mul_f32_e32 v136, s68, v66
	v_mul_f32_e32 v137, s68, v67
	v_exp_f32_e32 v138, v138
	v_mul_f32_e64 v139, |v136|, s54
	v_add_f32_e32 v70, 1.0, v70
	v_exp_f32_e32 v139, v139
	v_add_f32_e32 v72, 1.0, v72
	v_add_f32_e32 v131, 1.0, v131
	v_add_f32_e32 v138, 1.0, v138
	v_log_f32_e32 v70, v70
	v_add_f32_e32 v139, 1.0, v139
	v_log_f32_e32 v72, v72
	v_log_f32_e32 v131, v131
	v_log_f32_e32 v138, v138
	v_mov_b32_e32 v142, v139
	v_mul_f32_e32 v139, 0x3f317217, v70
	v_mul_f32_e32 v140, 0x3f317217, v72
	v_fma_f32 v139, v70, s86, -v139
	v_mul_f32_e32 v141, 0x3f317217, v131
	v_fma_f32 v140, v72, s86, -v140
	v_fmac_f32_e32 v139, 0x3377d1cf, v70
	v_mul_f32_e32 v143, 0x3f317217, v138
	v_fma_f32 v141, v131, s86, -v141
	v_fmac_f32_e32 v140, 0x3377d1cf, v72
	v_fmac_f32_e32 v139, 0x3f317217, v70
	v_fma_f32 v143, v138, s86, -v143
	v_fmac_f32_e32 v141, 0x3377d1cf, v131
	v_fmac_f32_e32 v140, 0x3f317217, v72
	v_fmac_f32_e32 v143, 0x3377d1cf, v138
	v_fmac_f32_e32 v141, 0x3f317217, v131
	v_fmac_f32_e32 v143, 0x3f317217, v138
	v_mov_b32_e32 v131, v141
	v_min_f32_e32 v132, 0, v132
	v_min_f32_e32 v133, 0, v133
	v_mov_b32_e32 v138, v139
	v_mov_b32_e32 v139, v131
	v_sub_f32_e32 v166, v132, v138
	v_sub_f32_e32 v167, v133, v139
	v_fma_f32 v174, -v64, s68, v166
	v_fma_f32 v175, -v65, s68, v167
	v_log_f32_e32 v65, v142
	v_min_f32_e32 v134, 0, v134
	v_min_f32_e32 v135, 0, v135
	v_mov_b32_e32 v141, v143
	v_sub_f32_e32 v164, v134, v140
	v_sub_f32_e32 v165, v135, v141
	v_mov_b32_e32 v72, v71
	v_fma_f32 v172, -v68, s68, v164
	v_fma_f32 v173, -v69, s68, v165
	v_mul_f32_e32 v68, 0x3f317217, v65
	v_fma_f32 v70, v65, s86, -v68
	v_mul_f32_e32 v68, s68, v72
	v_mul_f32_e32 v69, s68, v73
	v_fmac_f32_e32 v70, 0x3377d1cf, v65
	v_mul_f32_e64 v71, |v68|, s54
	v_exp_f32_e32 v71, v71
	v_fmac_f32_e32 v70, 0x3f317217, v65
	v_mul_f32_e64 v131, |v137|, s54
	v_exp_f32_e32 v131, v131
	v_mov_b32_e32 v65, v70
	v_add_f32_e32 v70, 1.0, v71
	v_mul_f32_e64 v133, |v69|, s54
	v_exp_f32_e32 v133, v133
	v_log_f32_e32 v71, v70
	v_mov_b32_e32 v70, v65
	v_min_f32_e32 v64, 0, v136
	v_mul_f32_e32 v65, 0x3f317217, v71
	v_fma_f32 v65, v71, s86, -v65
	v_fmac_f32_e32 v65, 0x3377d1cf, v71
	v_fmac_f32_e32 v65, 0x3f317217, v71
	v_min_f32_e32 v68, 0, v68
	v_min_f32_e32 v69, 0, v69
	v_add_f32_e32 v71, 1.0, v131
	v_mov_b32_e32 v140, v78
	v_mov_b32_e32 v141, v80
	v_log_f32_e32 v71, v71
	v_mov_b32_e32 v132, v65
	v_min_f32_e32 v65, 0, v137
	v_mul_f32_e32 v131, 0x3f317217, v71
	v_fma_f32 v131, v71, s86, -v131
	v_fmac_f32_e32 v131, 0x3377d1cf, v71
	v_fmac_f32_e32 v131, 0x3f317217, v71
	v_mul_f32_e32 v142, s68, v140
	v_mul_f32_e32 v143, s68, v141
	v_mov_b32_e32 v80, v79
	v_mov_b32_e32 v71, v131
	v_mov_b32_e32 v71, v71
	v_add_f32_e32 v131, 1.0, v133
	v_sub_f32_e32 v168, v64, v70
	v_sub_f32_e32 v169, v65, v71
	v_mov_b32_e32 v65, v76
	v_log_f32_e32 v131, v131
	v_fma_f32 v176, -v66, s68, v168
	v_fma_f32 v177, -v67, s68, v169
	v_mov_b32_e32 v76, v75
	v_mul_f32_e32 v144, s68, v80
	v_mul_f32_e32 v145, s68, v81
	v_mul_f32_e32 v64, 0x3f317217, v131
	v_fma_f32 v70, v131, s86, -v64
	v_mov_b32_e32 v64, v74
	v_mul_f32_e32 v66, s68, v64
	v_mul_f32_e32 v67, s68, v65
	v_fmac_f32_e32 v70, 0x3377d1cf, v131
	v_mul_f32_e64 v71, |v66|, s54
	v_exp_f32_e32 v71, v71
	v_fmac_f32_e32 v70, 0x3f317217, v131
	v_min_f32_e32 v66, 0, v66
	v_mov_b32_e32 v133, v70
	v_add_f32_e32 v70, 1.0, v71
	v_sub_f32_e32 v170, v68, v132
	v_sub_f32_e32 v171, v69, v133
	ds_read_b128 v[132:135], v130 offset:32
	v_log_f32_e32 v70, v70
	v_fma_f32 v178, -v72, s68, v170
	v_fma_f32 v179, -v73, s68, v171
	v_mul_f32_e64 v73, |v67|, s54
	v_exp_f32_e32 v73, v73
	v_mul_f32_e32 v68, 0x3f317217, v70
	v_fma_f32 v71, v70, s86, -v68
	v_mul_f32_e32 v68, s68, v76
	v_mul_f32_e32 v69, s68, v77
	v_fmac_f32_e32 v71, 0x3377d1cf, v70
	v_mul_f32_e64 v72, |v68|, s54
	v_exp_f32_e32 v72, v72
	v_fmac_f32_e32 v71, 0x3f317217, v70
	v_mul_f32_e64 v74, |v69|, s54
	v_exp_f32_e32 v74, v74
	v_mov_b32_e32 v70, v71
	v_add_f32_e32 v71, 1.0, v72
	v_min_f32_e32 v67, 0, v67
	v_min_f32_e32 v68, 0, v68
	v_log_f32_e32 v71, v71
	v_mov_b32_e32 v70, v70
	v_min_f32_e32 v69, 0, v69
	v_mul_f32_e32 v72, 0x3f317217, v71
	v_fma_f32 v72, v71, s86, -v72
	v_fmac_f32_e32 v72, 0x3377d1cf, v71
	v_fmac_f32_e32 v72, 0x3f317217, v71
	s_nop 1
	v_mov_b32_e32 v71, v72
	v_add_f32_e32 v72, 1.0, v73
	s_nop 1
	v_log_f32_e32 v73, v72
	v_mov_b32_e32 v72, v71
	v_mul_f32_e32 v71, 0x3f317217, v73
	v_fma_f32 v71, v73, s86, -v71
	v_fmac_f32_e32 v71, 0x3377d1cf, v73
	v_fmac_f32_e32 v71, 0x3f317217, v73
	s_nop 1
	v_add_f32_e32 v73, 1.0, v74
	v_sub_f32_e32 v180, v66, v70
	v_sub_f32_e32 v181, v67, v71
	v_mul_f32_e64 v70, |v143|, s54
	v_log_f32_e32 v73, v73
	v_fma_f32 v184, -v64, s68, v180
	v_fma_f32 v185, -v65, s68, v181
	v_mul_f32_e64 v65, |v142|, s54
	v_exp_f32_e32 v65, v65
	v_mul_f32_e32 v64, 0x3f317217, v73
	v_fma_f32 v64, v73, s86, -v64
	v_fmac_f32_e32 v64, 0x3377d1cf, v73
	v_fmac_f32_e32 v64, 0x3f317217, v73
	v_exp_f32_e32 v131, v70
	v_mov_b32_e32 v73, v64
	v_add_f32_e32 v64, 1.0, v65
	v_mul_f32_e64 v66, |v144|, s54
	v_exp_f32_e32 v66, v66
	v_log_f32_e32 v64, v64
	v_sub_f32_e32 v182, v68, v72
	v_sub_f32_e32 v183, v69, v73
	v_add_f32_e32 v131, 1.0, v131
	v_fma_f32 v186, -v76, s68, v182
	v_fma_f32 v187, -v77, s68, v183
	v_mul_f32_e32 v65, 0x3f317217, v64
	v_fma_f32 v65, v64, s86, -v65
	v_fmac_f32_e32 v65, 0x3377d1cf, v64
	v_fmac_f32_e32 v65, 0x3f317217, v64
	v_min_f32_e32 v142, 0, v142
	v_min_f32_e32 v143, 0, v143
	v_mov_b32_e32 v64, v65
	v_add_f32_e32 v65, 1.0, v66
	v_min_f32_e32 v144, 0, v144
	v_mov_b32_e32 v247, v180
	v_log_f32_e32 v68, v65
	v_mov_b32_e32 v146, v64
	ds_read_b128 v[64:67], v130
	v_mul_f32_e32 v69, 0x3f317217, v68
	v_fma_f32 v69, v68, s86, -v69
	v_fmac_f32_e32 v69, 0x3377d1cf, v68
	v_fmac_f32_e32 v69, 0x3f317217, v68
	s_nop 0
	v_mov_b32_e32 v147, v69
	s_waitcnt lgkmcnt(0)
	v_mfma_f32_32x32x16_bf16 v[64:79], v[64:67], v[82:85], 0
	v_mov_b32_e32 v148, v147
	s_nop 0
	ds_read_b128 v[136:139], v130 offset:64
	v_log_f32_e32 v131, v131
	v_mfma_f32_32x32x16_bf16 v[64:79], v[132:135], v[86:89], v[64:79]
	v_mul_f32_e32 v132, 0x3f317217, v131
	v_fma_f32 v147, v131, s86, -v132
	ds_read_b128 v[132:135], v130 offset:96
	v_fmac_f32_e32 v147, 0x3377d1cf, v131
	v_fmac_f32_e32 v147, 0x3f317217, v131
	s_waitcnt lgkmcnt(1)
	v_mfma_f32_32x32x16_bf16 v[64:79], v[136:139], v[90:93], v[64:79]
	v_mul_f32_e64 v137, |v145|, s54
	v_exp_f32_e32 v149, v137
	ds_read_b128 v[136:139], v130 offset:128
	s_waitcnt lgkmcnt(1)
	v_mfma_f32_32x32x16_bf16 v[64:79], v[132:135], v[94:97], v[64:79]
	v_add_f32_e32 v131, 1.0, v149
	v_add_f32_e64 v188, v142, -v146
	v_add_f32_e64 v189, v143, -v147
	v_min_f32_e32 v145, 0, v145
	ds_read_b128 v[132:135], v130 offset:160
	s_waitcnt lgkmcnt(1)
	v_mfma_f32_32x32x16_bf16 v[64:79], v[136:139], v[98:101], v[64:79]
	v_log_f32_e32 v131, v131
	v_fma_f32 v212, -v140, s68, v188
	v_fma_f32 v213, -v141, s68, v189
	v_mul_f32_e32 v136, 0x3f317217, v131
	v_fma_f32 v140, v131, s86, -v136
	ds_read_b128 v[136:139], v130 offset:192
	s_waitcnt lgkmcnt(1)
	v_mfma_f32_32x32x16_bf16 v[64:79], v[132:135], v[102:105], v[64:79]
	v_fmac_f32_e32 v140, 0x3377d1cf, v131
	v_fmac_f32_e32 v140, 0x3f317217, v131
	s_nop 0
	v_mov_b32_e32 v149, v140
	s_waitcnt lgkmcnt(0)
	v_mfma_f32_32x32x16_bf16 v[64:79], v[136:139], v[106:109], v[64:79]
	v_add_f32_e64 v190, v144, -v148
	v_add_f32_e64 v191, v145, -v149
	ds_read_b64_tr_b16 v[146:147], v207 offset:45056
	ds_read_b64_tr_b16 v[142:143], v207 offset:45120
	ds_read_b64_tr_b16 v[138:139], v207 offset:45184
	ds_read_b64_tr_b16 v[134:135], v207 offset:45248
	ds_read_b64_tr_b16 v[148:149], v207 offset:47616
	ds_read_b64_tr_b16 v[144:145], v207 offset:47680
	ds_read_b64_tr_b16 v[140:141], v207 offset:47744
	ds_read_b64_tr_b16 v[136:137], v207 offset:47808
	ds_read_b64_tr_b16 v[130:131], v207 offset:50176
	ds_read_b64_tr_b16 v[132:133], v207 offset:52736
	v_fma_f32 v216, -v80, s68, v190
	v_fma_f32 v217, -v81, s68, v191
	v_or_b32_e32 v80, 34, v163
	v_cmp_lt_i32_e64 s[26:27], v80, v153
	v_mfma_f32_32x32x16_bf16 v[64:79], v[208:211], v[110:113], v[64:79]
	v_or_b32_e32 v208, 32, v163
	v_cmp_lt_i32_e64 s[30:31], v208, v152
	v_or_b32_e32 v208, 33, v163
	v_cmp_lt_i32_e64 s[40:41], v208, v152
	v_cndmask_b32_e64 v80, 0, v174, s[30:31]
	v_or_b32_e32 v174, 35, v163
	v_cmp_lt_i32_e64 s[38:39], v174, v153
	v_cndmask_b32_e64 v81, 0, v175, s[26:27]
	v_cndmask_b32_e64 v174, 0, v172, s[40:41]
	v_cndmask_b32_e64 v175, 0, v173, s[38:39]
	v_add_f32_e32 v80, v80, v174
	v_add_f32_e32 v81, v81, v175
	v_or_b32_e32 v208, 40, v163
	v_add_f32_e32 v172, v80, v81
	v_add_f32_e32 v173, v81, v80
	v_cmp_lt_i32_e64 s[22:23], v208, v152
	v_or_b32_e32 v173, 42, v163
	v_cmp_lt_i32_e64 s[18:19], v173, v153
	v_or_b32_e32 v173, 43, v163
	v_or_b32_e32 v208, 41, v163
	v_cmp_lt_i32_e64 s[28:29], v173, v153
	v_or_b32_e32 v173, 50, v163
	v_cmp_lt_i32_e64 s[34:35], v208, v152
	v_or_b32_e32 v208, 48, v163
	v_cmp_lt_i32_e32 vcc, v173, v153
	v_or_b32_e32 v173, 51, v163
	v_cmp_lt_i32_e64 s[42:43], v208, v152
	v_or_b32_e32 v208, 49, v163
	v_cmp_lt_i32_e64 s[16:17], v173, v153
	v_or_b32_e32 v173, 58, v163
	v_cmp_lt_i32_e64 s[44:45], v208, v152
	v_or_b32_e32 v208, 56, v163
	v_cmp_lt_i32_e64 s[14:15], v173, v153
	v_or_b32_e32 v173, 59, v163
	v_or_b32_e32 v210, 57, v163
	v_cmp_lt_i32_e64 s[36:37], v208, v152
	v_cmp_lt_i32_e64 s[20:21], v173, v153
	v_cmp_lt_i32_e64 s[24:25], v210, v152
	v_cndmask_b32_e32 v185, 0, v185, vcc
	v_cndmask_b32_e64 v184, 0, v184, s[42:43]
	v_cndmask_b32_e64 v187, 0, v187, s[16:17]
	v_cndmask_b32_e64 v186, 0, v186, s[44:45]
	v_cndmask_b32_e64 v209, 0, v213, s[14:15]
	v_cndmask_b32_e64 v208, 0, v212, s[36:37]
	v_cndmask_b32_e64 v211, 0, v217, s[20:21]
	v_cndmask_b32_e64 v210, 0, v216, s[24:25]
	v_add_f32_e32 v184, v184, v186
	v_add_f32_e32 v185, v185, v187
	v_add_f32_e32 v208, v208, v210
	v_add_f32_e32 v209, v209, v211
	v_add_f32_e32 v240, v184, v185
	v_add_f32_e32 v241, v185, v184
	v_add_f32_e32 v212, v208, v209
	v_add_f32_e32 v213, v209, v208
	ds_bpermute_b32 v216, v235, v212
	ds_bpermute_b32 v184, v235, v240
	v_mov_b32_e32 v246, v186
	v_mov_b32_e32 v244, v185
	v_cndmask_b32_e64 v177, 0, v177, s[18:19]
	s_waitcnt lgkmcnt(1)
	v_add_f32_e32 v208, v212, v216
	s_waitcnt lgkmcnt(0)
	v_cndmask_b32_e64 v213, 0, v184, s[10:11]
	v_add_f32_e32 v208, v213, v208
	v_add_f32_e32 v245, v162, v208
	v_add_f32_e32 v246, v246, v244
	v_add_f32_e32 v247, v247, v245
	v_add_f32_e32 v182, v182, v245
	v_add_f32_e32 v180, v246, v247
	v_mul_f32_e32 v180, 0x3fb8aa3b, v180
	v_exp_f32_e32 v180, v180
	v_add_f32_e32 v182, v185, v182
	v_mul_f32_e32 v182, 0x3fb8aa3b, v182
	v_cndmask_b32_e64 v176, 0, v176, s[22:23]
	v_cndmask_b32_e64 v179, 0, v179, s[28:29]
	v_cndmask_b32_e64 v178, 0, v178, s[34:35]
	v_exp_f32_e32 v182, v182
	v_add_f32_e32 v176, v176, v178
	v_add_f32_e32 v177, v177, v179
	v_cndmask_b32_e64 v213, 0, v180, s[42:43]
	v_add_f32_e32 v180, v181, v245
	v_add_f32_e32 v242, v176, v177
	v_add_f32_e32 v243, v177, v176
	v_add_f32_e32 v180, v187, v180
	ds_bpermute_b32 v80, v235, v172
	ds_bpermute_b32 v176, v235, v242
	v_mul_f32_e32 v180, 0x3fb8aa3b, v180
	v_mov_b32_e32 v185, v240
	v_mov_b32_e32 v217, v212
	v_cndmask_b32_e64 v215, 0, v182, s[44:45]
	v_exp_f32_e32 v239, v180
	v_add_f32_e32 v180, v183, v245
	v_add_f32_e32 v182, v184, v216
	v_add_f32_e32 v183, v185, v217
	v_add_f32_e32 v180, 0, v180
	v_add_f32_e32 v181, v242, v183
	v_add_f32_e32 v181, v181, v216
	v_add_f32_e32 v181, v181, v184
	v_cndmask_b32_e64 v173, 0, v216, s[10:11]
	s_waitcnt lgkmcnt(1)
	v_cndmask_b32_e64 v208, 0, v80, s[10:11]
	v_mul_f32_e32 v180, 0x3fb8aa3b, v180
	s_waitcnt lgkmcnt(0)
	v_add_f32_e32 v181, v181, v176
	v_exp_f32_e32 v241, v180
	v_add_f32_e32 v180, v162, v173
	v_add_f32_e32 v173, v183, v216
	v_add_f32_e32 v181, v208, v181
	v_cndmask_b32_e64 v186, 0, v176, s[10:11]
	v_add_f32_e32 v173, v173, v184
	v_add_f32_e32 v185, v162, v181
	v_add_f32_e32 v173, v186, v173
	v_mov_b32_e32 v186, v174
	v_mov_b32_e32 v187, v166
	v_mov_b32_e32 v184, v81
	v_add_f32_e32 v164, v164, v185
	v_add_f32_e32 v186, v186, v184
	v_add_f32_e32 v187, v187, v185
	v_add_f32_e32 v81, v81, v164
	v_add_f32_e32 v164, v167, v185
	v_add_f32_e32 v165, v165, v185
	v_add_f32_e32 v166, v186, v187
	v_add_f32_e32 v164, v175, v164
	v_add_f32_e32 v165, 0, v165
	v_mul_f32_e32 v166, 0x3fb8aa3b, v166
	v_mul_f32_e32 v164, 0x3fb8aa3b, v164
	v_mul_f32_e32 v165, 0x3fb8aa3b, v165
	v_exp_f32_e32 v166, v166
	v_exp_f32_e32 v164, v164
	v_exp_f32_e32 v165, v165
	v_mov_b32_e32 v167, v168
	v_cndmask_b32_e64 v174, 0, v166, s[30:31]
	v_cndmask_b32_e64 v175, 0, v164, s[26:27]
	v_cndmask_b32_e64 v181, 0, v165, s[38:39]
	v_add_f32_e32 v165, v162, v173
	v_mov_b32_e32 v166, v178
	v_mov_b32_e32 v164, v177
	v_add_f32_e32 v166, v166, v164
	v_add_f32_e32 v167, v167, v165
	v_mul_f32_e32 v81, 0x3fb8aa3b, v81
	v_add_f32_e32 v164, v166, v167
	v_add_f32_e32 v166, v170, v165
	v_add_f32_e32 v167, v169, v165
	v_add_f32_e32 v165, v171, v165
	v_add_f32_e32 v166, v177, v166
	v_add_f32_e32 v167, v179, v167
	v_add_f32_e32 v165, 0, v165
	v_mul_f32_e32 v164, 0x3fb8aa3b, v164
	v_mul_f32_e32 v166, 0x3fb8aa3b, v166
	v_mul_f32_e32 v167, 0x3fb8aa3b, v167
	v_mul_f32_e32 v165, 0x3fb8aa3b, v165
	v_exp_f32_e32 v81, v81
	v_exp_f32_e32 v164, v164
	v_exp_f32_e32 v166, v166
	v_exp_f32_e32 v167, v167
	v_exp_f32_e32 v165, v165
	v_cndmask_b32_e64 v81, 0, v81, s[40:41]
	v_cndmask_b32_e64 v168, 0, v164, s[22:23]
	v_cndmask_b32_e64 v166, 0, v166, s[34:35]
	v_cndmask_b32_e64 v167, 0, v167, s[18:19]
	v_cndmask_b32_e64 v169, 0, v165, s[28:29]
	v_cvt_pk_bf16_f32 v164, v174, v81
	v_cvt_pk_bf16_f32 v165, v175, v181
	v_cvt_pk_bf16_f32 v166, v168, v166
	v_cvt_pk_bf16_f32 v167, v167, v169
	v_mov_b32_e32 v181, v210
	v_mov_b32_e32 v208, v188
	v_mfma_f32_32x32x16_bf16 v[48:63], v[146:149], v[164:167], v[48:63]
	v_add_f32_e64 v146, v180, v208
	v_add_f32_e64 v147, v181, v209
	v_mov_b32_e32 v177, v242
	v_add_f32_e32 v81, v146, v147
	v_mul_f32_e32 v81, 0x3fb8aa3b, v81
	v_exp_f32_e32 v81, v81
	v_cndmask_b32_e32 v146, 0, v239, vcc
	v_cndmask_b32_e64 v81, 0, v81, s[36:37]
	v_mfma_f32_32x32x16_bf16 v[32:47], v[142:145], v[164:167], v[32:47]
	v_add_f32_e32 v143, v180, v190
	v_add_f32_e32 v144, v180, v189
	v_add_f32_e32 v143, v143, v209
	v_mul_f32_e32 v143, 0x3fb8aa3b, v143
	v_exp_f32_e32 v143, v143
	v_cndmask_b32_e64 v142, 0, v241, s[16:17]
	v_mfma_f32_32x32x16_bf16 v[16:31], v[138:141], v[164:167], v[16:31]
	v_add_f32_e32 v139, v180, v191
	v_add_f32_e32 v138, v144, v211
	v_add_f32_e32 v139, 0, v139
	v_mul_f32_e32 v138, 0x3fb8aa3b, v138
	v_mul_f32_e32 v139, 0x3fb8aa3b, v139
	v_exp_f32_e32 v138, v138
	v_exp_f32_e32 v139, v139
	v_mfma_f32_32x32x16_bf16 v[0:15], v[134:137], v[164:167], v[0:15]
	v_cndmask_b32_e64 v136, 0, v143, s[24:25]
	v_cndmask_b32_e64 v137, 0, v138, s[14:15]
	v_cndmask_b32_e64 v138, 0, v139, s[20:21]
	v_cvt_pk_bf16_f32 v134, v213, v215
	v_cvt_pk_bf16_f32 v135, v146, v142
	v_cvt_pk_bf16_f32 v136, v81, v136
	v_cvt_pk_bf16_f32 v137, v137, v138
	ds_read_b64_tr_b16 v[138:139], v207 offset:50240
	ds_read_b64_tr_b16 v[142:143], v207 offset:50304
	ds_read_b64_tr_b16 v[146:147], v207 offset:50368
	ds_read_b64_tr_b16 v[140:141], v207 offset:52800
	ds_read_b64_tr_b16 v[144:145], v207 offset:52864
	ds_read_b64_tr_b16 v[148:149], v207 offset:52928
	v_mfma_f32_32x32x16_bf16 v[48:63], v[130:133], v[134:137], v[48:63]
	v_mov_b32_e32 v130, v64
	v_mov_b32_e32 v131, v68
	v_mul_f32_e64 v132, v130, s68
	v_mul_f32_e64 v133, v131, s68
	v_mov_b32_e32 v81, v172
	v_mul_f32_e64 v64, |v132|, s54
	v_exp_f32_e32 v64, v64
	v_add_f32_e32 v80, v80, v176
	v_add_f32_e32 v81, v81, v177
	s_waitcnt lgkmcnt(2)
	v_mfma_f32_32x32x16_bf16 v[32:47], v[138:141], v[134:137], v[32:47]
	v_add_f32_e64 v80, v80, v182
	v_add_f32_e64 v81, v81, v183
	v_add_f32_e32 v64, 1.0, v64
	s_nop 1
	v_log_f32_e32 v138, v64
	v_min_f32_e32 v64, 0, v132
	s_waitcnt lgkmcnt(1)
	v_mfma_f32_32x32x16_bf16 v[16:31], v[142:145], v[134:137], v[16:31]
	v_mul_f32_e64 v143, |v133|, s54
	v_mul_f32_e32 v68, 0x3f317217, v138
	v_fma_f32 v132, v138, s86, -v68
	v_mov_b32_e32 v68, v65
	v_fmac_f32_e32 v132, 0x3377d1cf, v138
	v_fmac_f32_e32 v132, 0x3f317217, v138
	s_waitcnt lgkmcnt(0)
	v_mfma_f32_32x32x16_bf16 v[0:15], v[146:149], v[134:137], v[0:15]
	v_mul_f32_e64 v134, v68, s68
	v_mul_f32_e64 v135, v69, s68
	v_mul_f32_e64 v65, |v134|, s54
	v_exp_f32_e32 v65, v65
	v_mov_b32_e32 v137, v70
	v_exp_f32_e32 v143, v143
	v_min_f32_e32 v134, 0, v134
	v_add_f32_e32 v65, 1.0, v65
	v_add_f32_e32 v143, 1.0, v143
	s_nop 0
	v_log_f32_e32 v65, v65
	s_nop 0
	v_mul_f32_e32 v136, 0x3f317217, v65
	v_fma_f32 v140, v65, s86, -v136
	v_mov_b32_e32 v136, v66
	v_mul_f32_e32 v138, s68, v136
	v_mul_f32_e32 v139, s68, v137
	v_fmac_f32_e32 v140, 0x3377d1cf, v65
	v_mul_f32_e64 v66, |v138|, s54
	v_exp_f32_e32 v66, v66
	v_fmac_f32_e32 v140, 0x3f317217, v65
	v_min_f32_e32 v138, 0, v138
	v_add_f32_e32 v66, 1.0, v66
	v_mov_b32_e32 v65, v140
	s_nop 1
	v_log_f32_e32 v142, v66
	v_mov_b32_e32 v70, v67
	v_mul_f32_e32 v140, s68, v70
	v_mul_f32_e32 v141, s68, v71
	v_mul_f32_e64 v67, |v140|, s54
	v_exp_f32_e32 v67, v67
	v_mov_b32_e32 v66, v65
	v_mul_f32_e32 v65, 0x3f317217, v142
	v_fma_f32 v65, v142, s86, -v65
	v_fmac_f32_e32 v65, 0x3377d1cf, v142
	v_fmac_f32_e32 v65, 0x3f317217, v142
	v_add_f32_e32 v67, 1.0, v67
	v_min_f32_e32 v140, 0, v140
	s_nop 1
	v_log_f32_e32 v67, v67
	v_mov_b32_e32 v142, v65
	v_mul_f32_e32 v65, 0x3f317217, v67
	v_fma_f32 v65, v67, s86, -v65
	v_fmac_f32_e32 v65, 0x3377d1cf, v67
	v_fmac_f32_e32 v65, 0x3f317217, v67
	s_nop 1
	s_nop 0
	v_log_f32_e32 v143, v143
	v_mov_b32_e32 v144, v65
	v_min_f32_e32 v65, 0, v133
	v_or_b32_e32 v67, 8, v163
	v_mul_f32_e32 v133, 0x3f317217, v143
	v_fma_f32 v133, v143, s86, -v133
	v_fmac_f32_e32 v133, 0x3377d1cf, v143
	v_fmac_f32_e32 v133, 0x3f317217, v143
	s_nop 1
	v_sub_f32_e32 v64, v64, v132
	v_sub_f32_e32 v65, v65, v133
	v_mul_f32_e64 v132, |v135|, s54
	v_exp_f32_e32 v132, v132
	v_cmp_lt_i32_e32 vcc, v67, v153
	v_fma_f32 v130, -v130, s68, v64
	v_fma_f32 v131, -v131, s68, v65
	v_cmp_lt_i32_e64 s[14:15], v163, v152
	v_add_f32_e32 v67, 1.0, v132
	s_nop 0
	v_cndmask_b32_e64 v146, 0, v130, s[14:15]
	v_min_f32_e32 v135, 0, v135
	v_log_f32_e32 v67, v67
	v_cndmask_b32_e32 v147, 0, v131, vcc
	v_or_b32_e32 v131, 1, v163
	v_or_b32_e32 v130, 9, v163
	v_mul_f32_e32 v132, 0x3f317217, v67
	v_fma_f32 v132, v67, s86, -v132
	v_fmac_f32_e32 v132, 0x3377d1cf, v67
	v_fmac_f32_e32 v132, 0x3f317217, v67
	s_nop 1
	v_mov_b32_e32 v67, v132
	v_mov_b32_e32 v67, v67
	v_mul_f32_e64 v132, |v139|, s54
	v_sub_f32_e32 v66, v134, v66
	v_sub_f32_e32 v67, v135, v67
	v_exp_f32_e32 v134, v132
	v_fma_f32 v68, -v68, s68, v66
	v_fma_f32 v69, -v69, s68, v67
	v_cmp_lt_i32_e64 s[18:19], v131, v152
	v_cmp_lt_i32_e64 s[16:17], v130, v153
	v_min_f32_e32 v139, 0, v139
	v_cndmask_b32_e64 v132, 0, v68, s[18:19]
	v_add_f32_e32 v68, 1.0, v134
	v_cndmask_b32_e64 v133, 0, v69, s[16:17]
	v_or_b32_e32 v135, 2, v163
	v_log_f32_e32 v68, v68
	v_cmp_lt_i32_e64 s[24:25], v135, v152
	v_or_b32_e32 v134, 10, v163
	v_mul_f32_e32 v69, 0x3f317217, v68
	v_fma_f32 v69, v68, s86, -v69
	v_fmac_f32_e32 v69, 0x3377d1cf, v68
	v_fmac_f32_e32 v69, 0x3f317217, v68
	s_nop 1
	v_mov_b32_e32 v68, v69
	v_mov_b32_e32 v143, v68
	v_sub_f32_e32 v68, v138, v142
	v_sub_f32_e32 v69, v139, v143
	v_cmp_lt_i32_e64 s[22:23], v134, v153
	v_fma_f32 v130, -v136, s68, v68
	v_fma_f32 v131, -v137, s68, v69
	v_mul_f32_e64 v136, |v141|, s54
	v_exp_f32_e32 v136, v136
	v_cndmask_b32_e64 v142, 0, v130, s[24:25]
	v_cndmask_b32_e64 v143, 0, v131, s[22:23]
	v_mul_f32_e32 v134, s68, v72
	v_mul_f32_e32 v135, s68, v73
	v_add_f32_e32 v130, 1.0, v136
	v_mul_f32_e64 v138, |v134|, s54
	v_exp_f32_e32 v138, v138
	v_log_f32_e32 v130, v130
	v_or_b32_e32 v136, 11, v163
	v_or_b32_e32 v137, 3, v163
	v_cmp_lt_i32_e64 s[34:35], v137, v152
	v_mul_f32_e32 v131, 0x3f317217, v130
	v_fma_f32 v131, v130, s86, -v131
	v_fmac_f32_e32 v131, 0x3377d1cf, v130
	v_fmac_f32_e32 v131, 0x3f317217, v130
	v_min_f32_e32 v134, 0, v134
	v_min_f32_e32 v141, 0, v141
	v_mov_b32_e32 v130, v131
	v_cmp_lt_i32_e64 s[26:27], v136, v153
	v_add_f32_e32 v136, 1.0, v138
	v_mov_b32_e32 v145, v130
	v_sub_f32_e32 v130, v140, v144
	v_sub_f32_e32 v131, v141, v145
	v_log_f32_e32 v136, v136
	v_mul_f32_e64 v138, |v135|, s54
	v_exp_f32_e32 v138, v138
	v_min_f32_e32 v135, 0, v135
	v_mul_f32_e32 v137, 0x3f317217, v136
	v_fma_f32 v137, v136, s86, -v137
	v_fmac_f32_e32 v137, 0x3377d1cf, v136
	v_fmac_f32_e32 v137, 0x3f317217, v136
	v_or_b32_e32 v140, 16, v163
	v_cmp_lt_i32_e64 s[36:37], v140, v152
	v_mov_b32_e32 v136, v137
	v_add_f32_e32 v137, 1.0, v138
	v_fma_f32 v70, -v70, s68, v130
	v_fma_f32 v71, -v71, s68, v131
	s_nop 0
	v_log_f32_e32 v137, v137
	v_mov_b32_e32 v136, v136
	v_cndmask_b32_e64 v71, 0, v71, s[26:27]
	v_mul_f32_e32 v138, 0x3f317217, v137
	v_fma_f32 v138, v137, s86, -v138
	v_fmac_f32_e32 v138, 0x3377d1cf, v137
	v_fmac_f32_e32 v138, 0x3f317217, v137
	v_cndmask_b32_e64 v70, 0, v70, s[34:35]
	s_nop 0
	v_mov_b32_e32 v137, v138
	v_mov_b32_e32 v137, v137
	v_sub_f32_e32 v134, v134, v136
	v_sub_f32_e32 v135, v135, v137
	v_mul_f32_e32 v136, s68, v74
	v_mul_f32_e32 v137, s68, v75
	v_or_b32_e32 v138, 17, v163
	v_mul_f32_e64 v139, |v136|, s54
	v_exp_f32_e32 v139, v139
	v_cmp_lt_i32_e64 s[20:21], v138, v153
	v_mul_f32_e64 v140, |v137|, s54
	v_exp_f32_e32 v140, v140
	v_add_f32_e32 v138, 1.0, v139
	v_min_f32_e32 v136, 0, v136
	v_min_f32_e32 v137, 0, v137
	v_log_f32_e32 v138, v138
	v_fma_f32 v72, -v72, s68, v134
	v_fma_f32 v73, -v73, s68, v135
	v_mul_f32_e32 v139, 0x3f317217, v138
	v_fma_f32 v139, v138, s86, -v139
	v_fmac_f32_e32 v139, 0x3377d1cf, v138
	v_fmac_f32_e32 v139, 0x3f317217, v138
	v_cndmask_b32_e64 v73, 0, v73, s[20:21]
	v_cndmask_b32_e64 v72, 0, v72, s[36:37]
	v_mov_b32_e32 v138, v139
	v_add_f32_e32 v139, 1.0, v140
	s_nop 1
	v_log_f32_e32 v139, v139
	v_mov_b32_e32 v138, v138
	v_mul_f32_e32 v140, 0x3f317217, v139
	v_fma_f32 v140, v139, s86, -v140
	v_fmac_f32_e32 v140, 0x3377d1cf, v139
	v_fmac_f32_e32 v140, 0x3f317217, v139
	s_nop 1
	v_mov_b32_e32 v139, v140
	v_mov_b32_e32 v139, v139
	v_or_b32_e32 v140, 18, v163
	v_cmp_lt_i32_e64 s[30:31], v140, v152
	v_add_f32_e32 v140, v142, v70
	v_add_f32_e32 v141, v143, v71
	v_mov_b32_e32 v142, v76
	v_mov_b32_e32 v143, v78
	v_mul_f32_e32 v144, s68, v142
	v_mul_f32_e32 v145, s68, v143
	v_sub_f32_e32 v136, v136, v138
	v_sub_f32_e32 v137, v137, v139
	v_mul_f32_e64 v76, |v144|, s54
	v_exp_f32_e32 v78, v76
	v_or_b32_e32 v138, 19, v163
	v_fma_f32 v74, -v74, s68, v136
	v_fma_f32 v75, -v75, s68, v137
	v_cmp_lt_i32_e64 s[28:29], v138, v153
	v_cndmask_b32_e64 v138, 0, v74, s[30:31]
	v_mul_f32_e64 v149, |v145|, s54
	v_cndmask_b32_e64 v139, 0, v75, s[28:29]
	v_add_f32_e32 v74, v146, v132
	v_add_f32_e32 v75, v147, v133
	v_exp_f32_e32 v149, v149
	v_add_f32_e32 v146, v74, v140
	v_add_f32_e32 v147, v75, v141
	v_add_f32_e32 v74, 1.0, v78
	ds_bpermute_b32 v148, v235, v147
	ds_bpermute_b32 v76, v235, v146
	v_log_f32_e32 v75, v74
	v_mov_b32_e32 v74, v73
	v_mul_f32_e32 v78, 0x3f317217, v75
	v_add_f32_e32 v164, v72, v74
	v_add_f32_e32 v165, v73, v75
	v_min_f32_e32 v74, 0, v144
	v_fma_f32 v144, v75, s86, -v78
	v_mov_b32_e32 v78, v77
	v_mul_f32_e32 v166, s68, v78
	v_mul_f32_e32 v167, s68, v79
	v_fmac_f32_e32 v144, 0x3377d1cf, v75
	v_mul_f32_e64 v77, |v166|, s54
	v_exp_f32_e32 v77, v77
	v_fmac_f32_e32 v144, 0x3f317217, v75
	v_min_f32_e32 v166, 0, v166
	v_add_f32_e32 v77, 1.0, v77
	v_mov_b32_e32 v75, v144
	v_or_b32_e32 v165, 24, v163
	v_cmp_lt_i32_e64 s[42:43], v165, v152
	v_log_f32_e32 v77, v77
	v_mov_b32_e32 v144, v75
	v_mul_f32_e32 v75, 0x3f317217, v77
	v_fma_f32 v75, v77, s86, -v75
	v_fmac_f32_e32 v75, 0x3377d1cf, v77
	v_fmac_f32_e32 v75, 0x3f317217, v77
	s_nop 1
	v_mov_b32_e32 v168, v75
	v_add_f32_e32 v75, 1.0, v149
	v_or_b32_e32 v149, 26, v163
	s_nop 0
	v_log_f32_e32 v77, v75
	v_min_f32_e32 v75, 0, v145
	v_mul_f32_e32 v145, 0x3f317217, v77
	v_fma_f32 v145, v77, s86, -v145
	v_fmac_f32_e32 v145, 0x3377d1cf, v77
	v_fmac_f32_e32 v145, 0x3f317217, v77
	s_nop 1
	v_mov_b32_e32 v77, v145
	v_mov_b32_e32 v145, v77
	v_mul_f32_e64 v77, |v167|, s54
	v_exp_f32_e32 v77, v77
	v_sub_f32_e32 v74, v74, v144
	v_sub_f32_e32 v75, v75, v145
	v_min_f32_e32 v167, 0, v167
	v_cmp_lt_i32_e64 s[38:39], v149, v153
	v_add_f32_e32 v77, 1.0, v77
	v_or_b32_e32 v149, 27, v163
	v_or_b32_e32 v163, 25, v163
	v_log_f32_e32 v77, v77
	v_fma_f32 v142, -v142, s68, v74
	v_fma_f32 v143, -v143, s68, v75
	v_mul_f32_e32 v144, 0x3f317217, v77
	v_fma_f32 v144, v77, s86, -v144
	v_fmac_f32_e32 v144, 0x3377d1cf, v77
	v_fmac_f32_e32 v144, 0x3f317217, v77
	v_cndmask_b32_e64 v143, 0, v143, s[38:39]
	v_cndmask_b32_e64 v142, 0, v142, s[42:43]
	v_mov_b32_e32 v77, v144
	v_mov_b32_e32 v169, v77
	v_sub_f32_e32 v144, v166, v168
	v_sub_f32_e32 v145, v167, v169
	v_cmp_lt_i32_e64 s[40:41], v149, v153
	v_fma_f32 v78, -v78, s68, v144
	v_fma_f32 v79, -v79, s68, v145
	v_cmp_lt_i32_e64 s[44:45], v163, v152
	v_cndmask_b32_e64 v167, 0, v79, s[40:41]
	v_mov_b32_e32 v168, v132
	v_cndmask_b32_e64 v166, 0, v78, s[44:45]
	v_mov_b32_e32 v132, v139
	v_add_f32_e32 v142, v142, v166
	v_add_f32_e32 v143, v143, v167
	v_add_f32_e32 v170, v138, v132
	v_add_f32_e32 v171, v139, v133
	v_mov_b32_e32 v165, v142
	v_mov_b32_e32 v171, v143
	v_add_f32_e32 v164, v164, v170
	v_add_f32_e32 v165, v165, v171
	ds_bpermute_b32 v149, v235, v165
	ds_bpermute_b32 v77, v235, v164
	v_add_f32_e32 v78, v146, v146
	v_add_f32_e32 v79, v146, v147
	v_mov_b32_e32 v169, v64
	v_mov_b32_e32 v64, v133
	v_add_f32_e32 v132, v164, v165
	v_add_f32_e32 v133, v165, v164
	s_waitcnt lgkmcnt(1)
	v_add_f32_e32 v142, v165, v149
	s_waitcnt lgkmcnt(0)
	v_cndmask_b32_e64 v146, 0, v77, s[10:11]
	v_add_f32_e32 v142, v146, v142
	v_add_f32_e32 v146, v132, v149
	v_add_f32_e32 v147, v147, v132
	v_add_f32_e32 v146, v146, v77
	v_cndmask_b32_e64 v163, 0, v148, s[10:11]
	v_add_f32_e32 v147, v147, v149
	v_add_f32_e32 v146, v163, v146
	v_add_f32_e32 v147, v147, v77
	v_cndmask_b32_e64 v163, 0, v76, s[10:11]
	v_add_f32_e32 v76, v76, v148
	v_add_f32_e32 v77, v77, v149
	v_mov_b32_e32 v78, v80
	v_add_f32_e32 v147, v147, v148
	v_add_f32_e32 v77, v76, v77
	v_add_f32_e32 v76, v76, v76
	v_pk_mov_b32 v[80:81], v[80:81], v[132:133] op_sel:[1,0]
	v_add_f32_e32 v147, v163, v147
	v_add_f32_e32 v78, v78, v80
	v_add_f32_e32 v79, v79, v81
	v_mov_b32_e32 v163, v77
	v_add_f32_e32 v80, v162, v78
	v_add_f32_e32 v81, v163, v79
	v_mov_b32_e32 v76, v140
	v_add_f32_e32 v77, v80, v147
	v_add_f32_e32 v78, v168, v76
	v_add_f32_e32 v79, v169, v77
	v_add_f32_e32 v68, v68, v77
	v_add_f32_e32 v76, v78, v79
	v_mul_f32_e32 v76, 0x3fb8aa3b, v76
	v_exp_f32_e32 v76, v76
	v_add_f32_e32 v66, v66, v77
	v_add_f32_e32 v68, v70, v68
	v_add_f32_e32 v70, v130, v77
	v_cndmask_b32_e64 v78, 0, v76, s[14:15]
	v_add_f32_e32 v77, v80, v146
	v_mov_b32_e32 v76, v141
	v_add_f32_e32 v66, v140, v66
	v_add_f32_e32 v64, v64, v76
	v_add_f32_e32 v65, v65, v77
	v_mul_f32_e32 v66, 0x3fb8aa3b, v66
	v_add_f32_e32 v64, v64, v65
	v_add_f32_e32 v65, v67, v77
	v_exp_f32_e32 v66, v66
	v_add_f32_e32 v65, v141, v65
	v_mul_f32_e32 v64, 0x3fb8aa3b, v64
	v_mul_f32_e32 v65, 0x3fb8aa3b, v65
	v_exp_f32_e32 v64, v64
	v_exp_f32_e32 v65, v65
	v_cndmask_b32_e64 v79, 0, v66, s[18:19]
	v_add_f32_e32 v66, v69, v77
	v_add_f32_e32 v66, v71, v66
	v_mul_f32_e32 v66, 0x3fb8aa3b, v66
	v_cndmask_b32_e32 v71, 0, v64, vcc
	v_cndmask_b32_e64 v76, 0, v65, s[16:17]
	v_add_f32_e32 v171, v80, v142
	v_pk_mov_b32 v[64:65], v[72:73], v[134:135] op_sel:[1,0]
	v_exp_f32_e32 v66, v66
	v_add_f32_e32 v67, v131, v77
	v_add_f32_e32 v64, v64, v170
	v_add_f32_e32 v65, v65, v171
	v_add_f32_e32 v67, 0, v67
	v_add_f32_e32 v64, v64, v65
	v_add_f32_e32 v65, v135, v171
	v_mul_f32_e32 v67, 0x3fb8aa3b, v67
	v_mul_f32_e32 v64, 0x3fb8aa3b, v64
	v_add_f32_e32 v65, v170, v65
	v_exp_f32_e32 v67, v67
	v_exp_f32_e32 v64, v64
	v_mul_f32_e32 v65, 0x3fb8aa3b, v65
	v_add_f32_e32 v70, 0, v70
	v_cndmask_b32_e64 v77, 0, v66, s[22:23]
	v_exp_f32_e32 v140, v65
	v_add_f32_e32 v65, v136, v171
	v_add_f32_e32 v66, v137, v171
	v_mul_f32_e32 v68, 0x3fb8aa3b, v68
	v_mul_f32_e32 v70, 0x3fb8aa3b, v70
	v_add_f32_e32 v65, v139, v65
	v_add_f32_e32 v66, 0, v66
	v_exp_f32_e32 v68, v68
	v_exp_f32_e32 v70, v70
	v_mul_f32_e32 v65, 0x3fb8aa3b, v65
	v_mul_f32_e32 v66, 0x3fb8aa3b, v66
	v_cndmask_b32_e64 v131, 0, v67, s[26:27]
	v_exp_f32_e32 v139, v66
	v_exp_f32_e32 v141, v65
	v_cndmask_b32_e64 v146, 0, v64, s[36:37]
	ds_read_b64_tr_b16 v[64:65], v207 offset:34816
	ds_read_b64_tr_b16 v[66:67], v207 offset:37376
	v_cndmask_b32_e64 v138, 0, v149, s[10:11]
	v_add_f32_e32 v72, v80, v138
	v_mov_b32_e32 v73, v166
	v_mov_b32_e32 v142, v74
	v_cndmask_b32_e64 v130, 0, v68, s[24:25]
	v_cndmask_b32_e64 v70, 0, v70, s[34:35]
	v_add_f32_e32 v68, v72, v142
	v_add_f32_e32 v69, v73, v143
	v_cndmask_b32_e64 v74, 0, v139, s[28:29]
	v_add_f32_e32 v73, v68, v69
	v_cvt_pk_bf16_f32 v68, v78, v79
	v_cvt_pk_bf16_f32 v69, v130, v70
	v_cvt_pk_bf16_f32 v70, v71, v76
	v_cvt_pk_bf16_f32 v71, v77, v131
	ds_read_b64_tr_b16 v[76:77], v207 offset:34880
	ds_read_b64_tr_b16 v[130:131], v207 offset:34944
	ds_read_b64_tr_b16 v[134:135], v207 offset:35008
	ds_read_b64_tr_b16 v[78:79], v207 offset:37440
	ds_read_b64_tr_b16 v[132:133], v207 offset:37504
	ds_read_b64_tr_b16 v[136:137], v207 offset:37568
	s_waitcnt lgkmcnt(6)
	v_mfma_f32_32x32x16_bf16 v[48:63], v[64:67], v[68:71], v[48:63]
	v_mul_f32_e32 v64, 0x3fb8aa3b, v73
	v_exp_f32_e32 v64, v64
	v_add_f32_e32 v65, v72, v75
	v_add_f32_e32 v65, v65, v167
	v_mul_f32_e32 v65, 0x3fb8aa3b, v65
	v_cndmask_b32_e64 v139, 0, v64, s[42:43]
	v_add_f32_e32 v64, v72, v144
	v_exp_f32_e32 v75, v65
	v_add_f32_e32 v65, v72, v145
	v_add_f32_e32 v64, v64, v143
	v_add_f32_e32 v65, 0, v65
	v_mul_f32_e32 v64, 0x3fb8aa3b, v64
	v_mul_f32_e32 v65, 0x3fb8aa3b, v65
	v_exp_f32_e32 v64, v64
	v_exp_f32_e32 v72, v65
	s_waitcnt lgkmcnt(2)
	v_mfma_f32_32x32x16_bf16 v[32:47], v[76:79], v[68:71], v[32:47]
	v_cndmask_b32_e64 v73, 0, v140, s[20:21]
	v_cndmask_b32_e64 v138, 0, v141, s[30:31]
	v_cndmask_b32_e64 v76, 0, v64, s[44:45]
	v_cndmask_b32_e64 v72, 0, v72, s[40:41]
	ds_read_b64_tr_b16 v[64:65], v207 offset:39936
	ds_read_b64_tr_b16 v[66:67], v207 offset:42496
	v_add_f32_e32 v162, v80, v81
	s_mov_b32 s14, 0xc2480000
	s_waitcnt lgkmcnt(3)
	v_mfma_f32_32x32x16_bf16 v[16:31], v[130:133], v[68:71], v[16:31]
	v_cmp_gt_f32_e32 vcc, s14, v162
	s_cmp_eq_u64 vcc, exec
	s_cselect_b64 s[14:15], -1, 0
	s_waitcnt lgkmcnt(2)
	v_mfma_f32_32x32x16_bf16 v[0:15], v[134:137], v[68:71], v[0:15]
	v_cndmask_b32_e64 v71, 0, v75, s[38:39]
	v_cvt_pk_bf16_f32 v68, v146, v73
	v_cvt_pk_bf16_f32 v69, v138, v74
	v_cvt_pk_bf16_f32 v70, v139, v76
	v_cvt_pk_bf16_f32 v71, v71, v72
	ds_read_b64_tr_b16 v[72:73], v207 offset:40000
	ds_read_b64_tr_b16 v[76:77], v207 offset:40064
	ds_read_b64_tr_b16 v[130:131], v207 offset:40128
	ds_read_b64_tr_b16 v[74:75], v207 offset:42560
	ds_read_b64_tr_b16 v[78:79], v207 offset:42624
	ds_read_b64_tr_b16 v[132:133], v207 offset:42688
	s_waitcnt lgkmcnt(6)
	v_mfma_f32_32x32x16_bf16 v[48:63], v[64:67], v[68:71], v[48:63]
	s_waitcnt lgkmcnt(2)
	v_mfma_f32_32x32x16_bf16 v[32:47], v[72:75], v[68:71], v[32:47]
	s_waitcnt lgkmcnt(1)
	v_mfma_f32_32x32x16_bf16 v[16:31], v[76:79], v[68:71], v[16:31]
	s_waitcnt lgkmcnt(0)
	v_mfma_f32_32x32x16_bf16 v[0:15], v[130:133], v[68:71], v[0:15]
